# P1 RMSNorm loop hand-rewritten: double-buffered x rows, per-batch modulation vectors hoisted, DPP wave reduction
# speedup vs baseline: 1.0163x; 1.0017x over previous
.LBB0_107:
	s_or_b64 exec, exec, s[4:5]
	s_load_dwordx16 s[36:51], s[0:1], 0x40
	s_cmpk_gt_i32 s64, 0x7fff
	v_lshlrev_b32_e32 v128, 2, v129
	v_mbcnt_lo_u32_b32 v165, -1, 0
	s_waitcnt lgkmcnt(0)
	s_barrier
	s_cbranch_scc1 .LBB0_110
	v_lshlrev_b32_e32 v96, 2, v128
	v_lshlrev_b32_e32 v97, 3, v129
	s_mov_b32 s65, s64
	s_lshl_b32 s13, s12, 12
	s_lshl_b32 s98, s12, 11
	s_lshl_b32 s0, s64, 12
	s_add_u32 s0, s16, s0
	s_addc_u32 s1, s17, 0
	s_lshl_b32 s4, s64, 11
	s_add_u32 s4, s62, s4
	s_addc_u32 s5, s63, 0
	s_add_u32 s4, s4, 0x2800000
	s_addc_u32 s5, s5, 0
	s_mov_b32 s99, -1
	global_load_dwordx4 v[0:3], v96, s[0:1] offset:0
	global_load_dwordx4 v[4:7], v96, s[0:1] offset:1024
	global_load_dwordx4 v[8:11], v96, s[0:1] offset:2048
	global_load_dwordx4 v[12:15], v96, s[0:1] offset:3072
	global_load_dwordx4 v[32:35], v96, s[24:25] offset:0
	global_load_dwordx4 v[36:39], v96, s[24:25] offset:1024
	global_load_dwordx4 v[40:43], v96, s[24:25] offset:2048
	global_load_dwordx4 v[44:47], v96, s[24:25] offset:3072
.Lp1_row_a:
	s_lshr_b32 s100, s65, 13
	s_cmp_eq_u32 s100, s99
	s_cbranch_scc1 .Lp1_nov_a
	s_mov_b32 s99, s100
	s_mul_i32 s100, s100, 0x6000
	s_add_u32 s8, s6, s100
	s_addc_u32 s9, s7, 0
	s_add_u32 s18, s8, 0x1000
	s_addc_u32 s19, s9, 0
	global_load_dwordx4 v[48:51], v96, s[18:19] offset:0
	global_load_dwordx4 v[52:55], v96, s[18:19] offset:1024
	global_load_dwordx4 v[56:59], v96, s[18:19] offset:2048
	global_load_dwordx4 v[60:63], v96, s[18:19] offset:3072
	global_load_dwordx4 v[64:67], v96, s[8:9] offset:0
	global_load_dwordx4 v[68:71], v96, s[8:9] offset:1024
	global_load_dwordx4 v[72:75], v96, s[8:9] offset:2048
	global_load_dwordx4 v[76:79], v96, s[8:9] offset:3072
	s_mov_b32 s101, 1
	s_branch .Lp1_pf_a
.Lp1_nov_a:
	s_mov_b32 s101, 0
.Lp1_pf_a:
	s_add_u32 s100, s65, s12
	s_cmp_lt_u32 s100, 0x8000
	s_cbranch_scc1 .Lp1_adv_a
	s_mov_b32 s18, s0
	s_mov_b32 s19, s1
	s_branch .Lp1_ld_a
.Lp1_adv_a:
	s_add_u32 s18, s0, s13
	s_addc_u32 s19, s1, 0
.Lp1_ld_a:
	global_load_dwordx4 v[16:19], v96, s[18:19] offset:0
	global_load_dwordx4 v[20:23], v96, s[18:19] offset:1024
	global_load_dwordx4 v[24:27], v96, s[18:19] offset:2048
	global_load_dwordx4 v[28:31], v96, s[18:19] offset:3072
	s_cmp_eq_u32 s101, 0
	s_cbranch_scc1 .Lp1_w8_a
	s_waitcnt vmcnt(4)
	v_add_f32_e32 v48, 1.0, v48
	v_add_f32_e32 v49, 1.0, v49
	v_add_f32_e32 v50, 1.0, v50
	v_add_f32_e32 v51, 1.0, v51
	v_add_f32_e32 v52, 1.0, v52
	v_add_f32_e32 v53, 1.0, v53
	v_add_f32_e32 v54, 1.0, v54
	v_add_f32_e32 v55, 1.0, v55
	v_add_f32_e32 v56, 1.0, v56
	v_add_f32_e32 v57, 1.0, v57
	v_add_f32_e32 v58, 1.0, v58
	v_add_f32_e32 v59, 1.0, v59
	v_add_f32_e32 v60, 1.0, v60
	v_add_f32_e32 v61, 1.0, v61
	v_add_f32_e32 v62, 1.0, v62
	v_add_f32_e32 v63, 1.0, v63
	s_branch .Lp1_go_a
.Lp1_w8_a:
	s_waitcnt vmcnt(8)
.Lp1_go_a:
	v_mul_f32_e32 v98, v0, v0
	v_fmac_f32_e32 v98, v1, v1
	v_fmac_f32_e32 v98, v2, v2
	v_fmac_f32_e32 v98, v3, v3
	v_fmac_f32_e32 v98, v4, v4
	v_fmac_f32_e32 v98, v5, v5
	v_fmac_f32_e32 v98, v6, v6
	v_fmac_f32_e32 v98, v7, v7
	v_fmac_f32_e32 v98, v8, v8
	v_fmac_f32_e32 v98, v9, v9
	v_fmac_f32_e32 v98, v10, v10
	v_fmac_f32_e32 v98, v11, v11
	v_fmac_f32_e32 v98, v12, v12
	v_fmac_f32_e32 v98, v13, v13
	v_fmac_f32_e32 v98, v14, v14
	v_fmac_f32_e32 v98, v15, v15
	s_nop 1
	v_add_f32_dpp v100, v98, v98 quad_perm:[1,0,3,2] row_mask:0xf bank_mask:0xf
	s_nop 1
	v_add_f32_dpp v98, v100, v100 quad_perm:[2,3,0,1] row_mask:0xf bank_mask:0xf
	s_nop 1
	v_add_f32_dpp v100, v98, v98 row_half_mirror row_mask:0xf bank_mask:0xf
	s_nop 1
	v_add_f32_dpp v98, v100, v100 row_mirror row_mask:0xf bank_mask:0xf
	s_nop 1
	v_readlane_b32 s100, v98, 0
	v_readlane_b32 s101, v98, 16
	v_readlane_b32 s18, v98, 32
	v_readlane_b32 s19, v98, 48
	s_nop 1
	v_mov_b32_e32 v100, s100
	v_add_f32_e32 v100, s101, v100
	v_mov_b32_e32 v98, s18
	v_add_f32_e32 v98, s19, v98
	v_add_f32_e32 v100, v100, v98
	v_mov_b32_e32 v98, 0x358637bd
	v_fmamk_f32 v100, v100, 0x3a800000, v98
	v_rsq_f32_e32 v99, v100
	s_nop 0
	v_mul_f32_e32 v0, v99, v0
	v_mul_f32_e32 v1, v99, v1
	v_mul_f32_e32 v2, v99, v2
	v_mul_f32_e32 v3, v99, v3
	v_mul_f32_e32 v4, v99, v4
	v_mul_f32_e32 v5, v99, v5
	v_mul_f32_e32 v6, v99, v6
	v_mul_f32_e32 v7, v99, v7
	v_mul_f32_e32 v8, v99, v8
	v_mul_f32_e32 v9, v99, v9
	v_mul_f32_e32 v10, v99, v10
	v_mul_f32_e32 v11, v99, v11
	v_mul_f32_e32 v12, v99, v12
	v_mul_f32_e32 v13, v99, v13
	v_mul_f32_e32 v14, v99, v14
	v_mul_f32_e32 v15, v99, v15
	v_mul_f32_e32 v0, v32, v0
	v_mul_f32_e32 v1, v33, v1
	v_mul_f32_e32 v2, v34, v2
	v_mul_f32_e32 v3, v35, v3
	v_mul_f32_e32 v4, v36, v4
	v_mul_f32_e32 v5, v37, v5
	v_mul_f32_e32 v6, v38, v6
	v_mul_f32_e32 v7, v39, v7
	v_mul_f32_e32 v8, v40, v8
	v_mul_f32_e32 v9, v41, v9
	v_mul_f32_e32 v10, v42, v10
	v_mul_f32_e32 v11, v43, v11
	v_mul_f32_e32 v12, v44, v12
	v_mul_f32_e32 v13, v45, v13
	v_mul_f32_e32 v14, v46, v14
	v_mul_f32_e32 v15, v47, v15
	v_fma_f32 v0, v48, v0, v64
	v_fma_f32 v1, v49, v1, v65
	v_fma_f32 v2, v50, v2, v66
	v_fma_f32 v3, v51, v3, v67
	v_fma_f32 v4, v52, v4, v68
	v_fma_f32 v5, v53, v5, v69
	v_fma_f32 v6, v54, v6, v70
	v_fma_f32 v7, v55, v7, v71
	v_fma_f32 v8, v56, v8, v72
	v_fma_f32 v9, v57, v9, v73
	v_fma_f32 v10, v58, v10, v74
	v_fma_f32 v11, v59, v11, v75
	v_fma_f32 v12, v60, v12, v76
	v_fma_f32 v13, v61, v13, v77
	v_fma_f32 v14, v62, v14, v78
	v_fma_f32 v15, v63, v15, v79
	v_cvt_pk_bf16_f32 v80, v0, v1
	v_cvt_pk_bf16_f32 v81, v2, v3
	v_cvt_pk_bf16_f32 v82, v4, v5
	v_cvt_pk_bf16_f32 v83, v6, v7
	v_cvt_pk_bf16_f32 v84, v8, v9
	v_cvt_pk_bf16_f32 v85, v10, v11
	v_cvt_pk_bf16_f32 v86, v12, v13
	v_cvt_pk_bf16_f32 v87, v14, v15
	global_store_dwordx2 v97, v[80:81], s[4:5] offset:0
	global_store_dwordx2 v97, v[82:83], s[4:5] offset:512
	global_store_dwordx2 v97, v[84:85], s[4:5] offset:1024
	global_store_dwordx2 v97, v[86:87], s[4:5] offset:1536
	s_add_u32 s65, s65, s12
	s_add_u32 s0, s0, s13
	s_addc_u32 s1, s1, 0
	s_add_u32 s4, s4, s98
	s_addc_u32 s5, s5, 0
	s_cmp_lt_u32 s65, 0x8000
	s_cbranch_scc0 .LBB0_110

.Lp1_ld_b:
	global_load_dwordx4 v[0:3], v96, s[18:19] offset:0
	global_load_dwordx4 v[4:7], v96, s[18:19] offset:1024
	global_load_dwordx4 v[8:11], v96, s[18:19] offset:2048
	global_load_dwordx4 v[12:15], v96, s[18:19] offset:3072
	s_cmp_eq_u32 s101, 0
	s_cbranch_scc1 .Lp1_w8_b
	s_waitcnt vmcnt(4)
	v_add_f32_e32 v48, 1.0, v48
	v_add_f32_e32 v49, 1.0, v49
	v_add_f32_e32 v50, 1.0, v50
	v_add_f32_e32 v51, 1.0, v51
	v_add_f32_e32 v52, 1.0, v52
	v_add_f32_e32 v53, 1.0, v53
	v_add_f32_e32 v54, 1.0, v54
	v_add_f32_e32 v55, 1.0, v55
	v_add_f32_e32 v56, 1.0, v56
	v_add_f32_e32 v57, 1.0, v57
	v_add_f32_e32 v58, 1.0, v58
	v_add_f32_e32 v59, 1.0, v59
	v_add_f32_e32 v60, 1.0, v60
	v_add_f32_e32 v61, 1.0, v61
	v_add_f32_e32 v62, 1.0, v62
	v_add_f32_e32 v63, 1.0, v63
	s_branch .Lp1_go_b

.Lp1_go_b:
	v_mul_f32_e32 v98, v16, v16
	v_fmac_f32_e32 v98, v17, v17
	v_fmac_f32_e32 v98, v18, v18
	v_fmac_f32_e32 v98, v19, v19
	v_fmac_f32_e32 v98, v20, v20
	v_fmac_f32_e32 v98, v21, v21
	v_fmac_f32_e32 v98, v22, v22
	v_fmac_f32_e32 v98, v23, v23
	v_fmac_f32_e32 v98, v24, v24
	v_fmac_f32_e32 v98, v25, v25
	v_fmac_f32_e32 v98, v26, v26
	v_fmac_f32_e32 v98, v27, v27
	v_fmac_f32_e32 v98, v28, v28
	v_fmac_f32_e32 v98, v29, v29
	v_fmac_f32_e32 v98, v30, v30
	v_fmac_f32_e32 v98, v31, v31
	s_nop 1
	v_add_f32_dpp v100, v98, v98 quad_perm:[1,0,3,2] row_mask:0xf bank_mask:0xf
	s_nop 1
	v_add_f32_dpp v98, v100, v100 quad_perm:[2,3,0,1] row_mask:0xf bank_mask:0xf
	s_nop 1
	v_add_f32_dpp v100, v98, v98 row_half_mirror row_mask:0xf bank_mask:0xf
	s_nop 1
	v_add_f32_dpp v98, v100, v100 row_mirror row_mask:0xf bank_mask:0xf
	s_nop 1
	v_readlane_b32 s100, v98, 0
	v_readlane_b32 s101, v98, 16
	v_readlane_b32 s18, v98, 32
	v_readlane_b32 s19, v98, 48
	s_nop 1
	v_mov_b32_e32 v100, s100
	v_add_f32_e32 v100, s101, v100
	v_mov_b32_e32 v98, s18
	v_add_f32_e32 v98, s19, v98
	v_add_f32_e32 v100, v100, v98
	v_mov_b32_e32 v98, 0x358637bd
	v_fmamk_f32 v100, v100, 0x3a800000, v98
	v_rsq_f32_e32 v99, v100
	s_nop 0
	v_mul_f32_e32 v16, v99, v16
	v_mul_f32_e32 v17, v99, v17
	v_mul_f32_e32 v18, v99, v18
	v_mul_f32_e32 v19, v99, v19
	v_mul_f32_e32 v20, v99, v20
	v_mul_f32_e32 v21, v99, v21
	v_mul_f32_e32 v22, v99, v22
	v_mul_f32_e32 v23, v99, v23
	v_mul_f32_e32 v24, v99, v24
	v_mul_f32_e32 v25, v99, v25
	v_mul_f32_e32 v26, v99, v26
	v_mul_f32_e32 v27, v99, v27
	v_mul_f32_e32 v28, v99, v28
	v_mul_f32_e32 v29, v99, v29
	v_mul_f32_e32 v30, v99, v30
	v_mul_f32_e32 v31, v99, v31
	v_mul_f32_e32 v16, v32, v16
	v_mul_f32_e32 v17, v33, v17
	v_mul_f32_e32 v18, v34, v18
	v_mul_f32_e32 v19, v35, v19
	v_mul_f32_e32 v20, v36, v20
	v_mul_f32_e32 v21, v37, v21
	v_mul_f32_e32 v22, v38, v22
	v_mul_f32_e32 v23, v39, v23
	v_mul_f32_e32 v24, v40, v24
	v_mul_f32_e32 v25, v41, v25
	v_mul_f32_e32 v26, v42, v26
	v_mul_f32_e32 v27, v43, v27
	v_mul_f32_e32 v28, v44, v28
	v_mul_f32_e32 v29, v45, v29
	v_mul_f32_e32 v30, v46, v30
	v_mul_f32_e32 v31, v47, v31
	v_fma_f32 v16, v48, v16, v64
	v_fma_f32 v17, v49, v17, v65
	v_fma_f32 v18, v50, v18, v66
	v_fma_f32 v19, v51, v19, v67
	v_fma_f32 v20, v52, v20, v68
	v_fma_f32 v21, v53, v21, v69
	v_fma_f32 v22, v54, v22, v70
	v_fma_f32 v23, v55, v23, v71
	v_fma_f32 v24, v56, v24, v72
	v_fma_f32 v25, v57, v25, v73
	v_fma_f32 v26, v58, v26, v74
	v_fma_f32 v27, v59, v27, v75
	v_fma_f32 v28, v60, v28, v76
	v_fma_f32 v29, v61, v29, v77
	v_fma_f32 v30, v62, v30, v78
	v_fma_f32 v31, v63, v31, v79
	v_cvt_pk_bf16_f32 v80, v16, v17
	v_cvt_pk_bf16_f32 v81, v18, v19
	v_cvt_pk_bf16_f32 v82, v20, v21
	v_cvt_pk_bf16_f32 v83, v22, v23
	v_cvt_pk_bf16_f32 v84, v24, v25
	v_cvt_pk_bf16_f32 v85, v26, v27
	v_cvt_pk_bf16_f32 v86, v28, v29
	v_cvt_pk_bf16_f32 v87, v30, v31
	global_store_dwordx2 v97, v[80:81], s[4:5] offset:0
	global_store_dwordx2 v97, v[82:83], s[4:5] offset:512
	global_store_dwordx2 v97, v[84:85], s[4:5] offset:1024
	global_store_dwordx2 v97, v[86:87], s[4:5] offset:1536
	s_add_u32 s65, s65, s12
	s_add_u32 s0, s0, s13
	s_addc_u32 s1, s1, 0
	s_add_u32 s4, s4, s98
	s_addc_u32 s5, s5, 0
	s_cmp_lt_u32 s65, 0x8000
	s_cbranch_scc1 .Lp1_row_a
